# M1 state-row copies (conv/shift states): one 16B load and two 16B stores per thread instead of 4 serialized 2-byte round trips
# speedup vs baseline: 1.0098x; 1.0098x over previous
; __device__ __forceinline__ float bf2f(bf16_t h) { return __uint_as_float((unsigned)h << 16); }
; __device__ __forceinline__ void phase_m1(PP P, int l, LAS unsigned char* lds, const Ids I) {
;     ...
;     for (int idx = BID * 512 + tid; idx < NMR * 3328; idx += NB * 512) {
;         const int m = idx / 3328, e = idx - m * 3328;
;         if (e < 1536) { const int j = e >> 9, ch = e & 511; const int row = (m < 8) ? m * 2048 + 2045 + j : MTP + (m - 8) * 4 + 1 + j; const float v = bf2f(PR[(size_t)row * INW + ch]);
;             if (m < 8) P->out[O_PCONV + (((size_t)l * 8 + m) * 3 + j) * 512 + ch] = v; else P->out[O_SCONV + (((size_t)l * 128 + (m - 8)) * 3 + j) * 512 + ch] = v; }
;         else { const int col = e - 1536; const int row = (m < 8) ? m * 2048 + 2047 : MTP + (m - 8) * 4 + 3; const float v = bf2f(PR[(size_t)row * INW + 1024 + col]);
;             if (m < 8) P->out[O_PSHIFT + ((size_t)l * 8 + m) * PW + col] = v; else P->out[O_SSHIFT + ((size_t)l * 128 + (m - 8)) * PW + col] = v; }
;     }
.LBB0_318:
	v_readlane_b32 s0, v254, 48
	s_barrier
	s_nop 0
	v_add_u32_e32 v2, s0, v96
	s_mov_b32 s0, 0xdd00
	v_cmp_gt_i32_e32 vcc, s0, v2
	s_mov_b64 s[4:5], exec
	v_readlane_b32 s68, v254, 11
	v_readlane_b32 s42, v254, 52
	v_readlane_b32 s36, v254, 50
	s_and_b64 s[0:1], s[4:5], vcc
	v_readlane_b32 s69, v254, 12
	s_movk_i32 s90, 0xb00
	v_readlane_b32 s47, v254, 54
	v_readlane_b32 s30, v254, 45
	v_readlane_b32 s25, v254, 49
	v_readlane_b32 s34, v254, 46
	v_readlane_b32 s27, v254, 47
	s_mov_b64 s[20:21], 0
	v_readlane_b32 s43, v254, 53
	v_readlane_b32 s37, v254, 51
	v_mov_b32_e32 v236, 0x2000
	v_mov_b32_e32 v237, 1
	v_mov_b32_e32 v238, 0xfffffc00
	v_mov_b32_e32 v241, 0x7fd
	s_mov_b64 exec, s[0:1]
	s_cbranch_execz .LBB0_333
	v_readlane_b32 s0, v254, 41
	s_lshl_b32 s0, s0, 3
	s_load_dwordx2 s[10:11], s[88:89], 0x140
	v_lshlrev_b32_e32 v3, 3, v2
	s_mov_b32 s1, 0x4ec4ec4f
	v_mul_hi_i32 v0, v3, s1
	v_lshrrev_b32_e32 v1, 31, v0
	v_ashrrev_i32_e32 v0, 10, v0
	v_add_u32_e32 v4, v0, v1
	s_movk_i32 s1, 0xf300
	v_mad_i32_i24 v5, v4, s1, v3
	s_movk_i32 s1, 0x5ff
	v_cmp_lt_i32_e64 s[6:7], s1, v5
	s_movk_i32 s1, 0x6800
	v_cmp_gt_i32_e64 s[8:9], s1, v3
	v_ashrrev_i32_e32 v6, 9, v5
	v_and_b32_e32 v7, 0x1ff, v5
	v_add_u32_e32 v8, 0xfffffa00, v5
	v_lshlrev_b32_e32 v9, 11, v4
	v_mov_b32_e32 v10, 0x3fe1
	v_lshl_add_u32 v10, v4, 2, v10
	v_add_u32_e32 v9, 0x7fd, v9
	v_cndmask_b32_e64 v9, v10, v9, s[8:9]
	v_cndmask_b32_e64 v10, v6, 2, s[6:7]
	v_add_u32_e32 v9, v9, v10
	v_lshlrev_b32_e32 v11, 1, v7
	v_lshlrev_b32_e32 v12, 1, v8
	v_add_u32_e32 v12, 0x800, v12
	v_cndmask_b32_e64 v144, v11, v12, s[6:7]
	v_mov_b64_e32 v[0:1], s[60:61]
	v_mad_i64_i32 v[0:1], s[16:17], v9, s73, v[0:1]
	v_lshl_add_u64 v[0:1], v[0:1], 0, v[144:145]
	global_load_dwordx4 v[12:15], v[0:1], off
	v_add_u32_e32 v9, s0, v4
	v_add3_u32 v10, v4, s34, -8
	v_cndmask_b32_e64 v9, v10, v9, s[8:9]
	v_mad_u32_u24 v10, v9, 3, v6
	v_lshlrev_b32_e32 v10, 11, v10
	v_lshl_add_u32 v10, v7, 2, v10
	v_mul_u32_u24_e32 v11, 0x1c00, v9
	v_lshl_add_u32 v11, v8, 2, v11
	v_cndmask_b32_e64 v10, v10, v11, s[6:7]
	v_mov_b32_e32 v6, 0x443c000
	v_mov_b32_e32 v7, 0x4200000
	v_cndmask_b32_e64 v6, v6, v7, s[8:9]
	v_mov_b32_e32 v7, 0x463c000
	v_mov_b32_e32 v8, 0x4220000
	v_cndmask_b32_e64 v7, v7, v8, s[8:9]
	v_cndmask_b32_e64 v6, v6, v7, s[6:7]
	v_add_u32_e32 v144, v10, v6
	s_waitcnt lgkmcnt(0)
	v_lshl_add_u64 v[4:5], s[10:11], 0, v[144:145]
	s_waitcnt vmcnt(0)
	v_lshlrev_b32_e32 v0, 16, v12
	v_and_b32_e32 v1, 0xffff0000, v12
	v_lshlrev_b32_e32 v2, 16, v13
	v_and_b32_e32 v3, 0xffff0000, v13
	v_lshlrev_b32_e32 v8, 16, v14
	v_and_b32_e32 v9, 0xffff0000, v14
	v_lshlrev_b32_e32 v10, 16, v15
	v_and_b32_e32 v11, 0xffff0000, v15
	global_store_dwordx4 v[4:5], v[0:3], off
	global_store_dwordx4 v[4:5], v[8:11], off offset:16
	s_branch .LBB0_333
	s_nop 0
	s_nop 0
	s_nop 0
	s_nop 0
	s_nop 0
	s_nop 0
	s_nop 0
	s_nop 0
	s_nop 0
	s_nop 0
	s_nop 0
	s_nop 0
	s_nop 0
	s_nop 0
	s_nop 0
	s_nop 0
	s_nop 0
	s_nop 0
	s_nop 0
	s_nop 0
	s_nop 0
	s_nop 0
	s_nop 0
	s_nop 0
	s_nop 0
	s_nop 0
	s_nop 0
	s_nop 0
	s_nop 0
	s_nop 0
	s_nop 0
	s_nop 0
	s_nop 0
	s_nop 0
	s_nop 0
	s_nop 0
	s_nop 0
	s_nop 0
	s_nop 0
	s_nop 0
	s_nop 0
	s_nop 0
	s_nop 0
	s_nop 0
	s_nop 0
	s_nop 0
	s_nop 0
	s_nop 0
	s_nop 0
	s_nop 0
	s_nop 0
	s_nop 0
	s_nop 0
	s_nop 0
	s_nop 0
	s_nop 0
	s_nop 0
	s_nop 0
	s_nop 0
	s_nop 0
	s_nop 0
